# attention tile body: one lgkmcnt wait per two fragments, m0 writes hoisted (no s_nop)
# baseline (speedup 1.0000x reference)
.Lat_loop:
	s_waitcnt vmcnt(0) lgkmcnt(0)
	s_barrier
	s_cmp_gt_u32 s58, s89
	s_cbranch_scc1 .Lat_inactive
	ds_read_b128 v[162:165], v234
	ds_read_b128 v[166:169], v235
	ds_read_b128 v[170:173], v236
	ds_read_b128 v[174:177], v237
	v_add_u32_e32 v242, s70, v222
	s_add_i32 m0, s71, 0x0
	s_nop 0
	global_load_lds_dwordx4 v231, s[50:51]
	s_add_i32 m0, s71, 0x400
	s_nop 0
	global_load_lds_dwordx4 v229, s[50:51]
	s_waitcnt lgkmcnt(2)
	v_mfma_f32_16x16x32_bf16 v[130:133], v[162:165], v[178:181], v[246:249]
	v_mfma_f32_16x16x32_bf16 v[146:149], v[162:165], v[194:197], v[250:253]
	ds_read_b128 v[162:165], v234 offset:4096
	v_mfma_f32_16x16x32_bf16 v[130:133], v[166:169], v[182:185], v[130:133]
	s_add_i32 m0, s71, 0x800
	v_mfma_f32_16x16x32_bf16 v[146:149], v[166:169], v[198:201], v[146:149]
	ds_read_b128 v[166:169], v235 offset:4096
	global_load_lds_dwordx4 v227, s[50:51]
	s_waitcnt lgkmcnt(2)
	v_mfma_f32_16x16x32_bf16 v[130:133], v[170:173], v[186:189], v[130:133]
	v_mfma_f32_16x16x32_bf16 v[146:149], v[170:173], v[202:205], v[146:149]
	ds_read_b128 v[170:173], v236 offset:4096
	v_mfma_f32_16x16x32_bf16 v[130:133], v[174:177], v[190:193], v[130:133]
	s_add_i32 m0, s71, 0xc00
	v_mfma_f32_16x16x32_bf16 v[146:149], v[174:177], v[206:209], v[146:149]
	ds_read_b128 v[174:177], v237 offset:4096
	global_load_lds_dwordx4 v225, s[50:51]
	s_waitcnt lgkmcnt(2)
	v_mfma_f32_16x16x32_bf16 v[134:137], v[162:165], v[178:181], v[246:249]
	v_mfma_f32_16x16x32_bf16 v[150:153], v[162:165], v[194:197], v[250:253]
	ds_read_b128 v[162:165], v234 offset:8192
	v_mfma_f32_16x16x32_bf16 v[134:137], v[166:169], v[182:185], v[134:137]
	s_add_i32 m0, s71, 0x1000
	v_mfma_f32_16x16x32_bf16 v[150:153], v[166:169], v[198:201], v[150:153]
	ds_read_b128 v[166:169], v235 offset:8192
	global_load_lds_dwordx4 v230, s[50:51]
	s_waitcnt lgkmcnt(2)
	v_mfma_f32_16x16x32_bf16 v[134:137], v[170:173], v[186:189], v[134:137]
	v_mfma_f32_16x16x32_bf16 v[150:153], v[170:173], v[202:205], v[150:153]
	ds_read_b128 v[170:173], v236 offset:8192
	v_mfma_f32_16x16x32_bf16 v[134:137], v[174:177], v[190:193], v[134:137]
	s_add_i32 m0, s71, 0x1400
	v_mfma_f32_16x16x32_bf16 v[150:153], v[174:177], v[206:209], v[150:153]
	ds_read_b128 v[174:177], v237 offset:8192
	global_load_lds_dwordx4 v228, s[50:51]
	s_waitcnt lgkmcnt(2)
	v_mfma_f32_16x16x32_bf16 v[138:141], v[162:165], v[178:181], v[246:249]
	v_mfma_f32_16x16x32_bf16 v[154:157], v[162:165], v[194:197], v[250:253]
	ds_read_b128 v[162:165], v234 offset:12288
	v_mfma_f32_16x16x32_bf16 v[138:141], v[166:169], v[182:185], v[138:141]
	s_add_i32 m0, s71, 0x1800
	v_mfma_f32_16x16x32_bf16 v[154:157], v[166:169], v[198:201], v[154:157]
	ds_read_b128 v[166:169], v235 offset:12288
	global_load_lds_dwordx4 v226, s[50:51]
	s_waitcnt lgkmcnt(2)
	v_mfma_f32_16x16x32_bf16 v[138:141], v[170:173], v[186:189], v[138:141]
	v_mfma_f32_16x16x32_bf16 v[154:157], v[170:173], v[202:205], v[154:157]
	ds_read_b128 v[170:173], v236 offset:12288
	v_mfma_f32_16x16x32_bf16 v[138:141], v[174:177], v[190:193], v[138:141]
	s_add_i32 m0, s71, 0x1c00
	v_mfma_f32_16x16x32_bf16 v[154:157], v[174:177], v[206:209], v[154:157]
	ds_read_b128 v[174:177], v237 offset:12288
	global_load_lds_dwordx4 v224, s[50:51]
	s_waitcnt lgkmcnt(2)
	v_mfma_f32_16x16x32_bf16 v[142:145], v[162:165], v[178:181], v[246:249]
	v_mfma_f32_16x16x32_bf16 v[158:161], v[162:165], v[194:197], v[250:253]
	ds_read_b64_tr_b16 v[162:163], v242 offset:0
	ds_read_b64_tr_b16 v[164:165], v242 offset:8192
	v_mfma_f32_16x16x32_bf16 v[142:145], v[166:169], v[182:185], v[142:145]
	v_mfma_f32_16x16x32_bf16 v[158:161], v[166:169], v[198:201], v[158:161]
	ds_read_b64_tr_b16 v[166:167], v242 offset:16384
	ds_read_b64_tr_b16 v[168:169], v242 offset:24576
	s_waitcnt lgkmcnt(4)
	v_mfma_f32_16x16x32_bf16 v[142:145], v[170:173], v[186:189], v[142:145]
	v_mfma_f32_16x16x32_bf16 v[158:161], v[170:173], v[202:205], v[158:161]
	ds_read_b64_tr_b16 v[170:171], v242 offset:256
	ds_read_b64_tr_b16 v[172:173], v242 offset:8448
	v_mfma_f32_16x16x32_bf16 v[142:145], v[174:177], v[190:193], v[142:145]
	v_mfma_f32_16x16x32_bf16 v[158:161], v[174:177], v[206:209], v[158:161]
	ds_read_b64_tr_b16 v[174:175], v242 offset:16640
	ds_read_b64_tr_b16 v[176:177], v242 offset:24832
	s_add_i32 s4, s91, 0xb0
	s_cmp_le_u32 s4, s3
	s_cbranch_scc0 .Lat_diag_a

.Lat_exp_a:
	v_exp_f32_e32 v130, v130
	v_exp_f32_e32 v131, v131
	v_exp_f32_e32 v132, v132
	v_add_f32_e32 v0, v130, v131
	v_exp_f32_e32 v133, v133
	v_add_f32_e32 v0, v0, v132
	v_exp_f32_e32 v134, v134
	v_add_f32_e32 v0, v0, v133
	v_exp_f32_e32 v135, v135
	v_add_f32_e32 v0, v0, v134
	v_exp_f32_e32 v136, v136
	v_add_f32_e32 v0, v0, v135
	v_exp_f32_e32 v137, v137
	v_add_f32_e32 v0, v0, v136
	v_exp_f32_e32 v138, v138
	v_add_f32_e32 v0, v0, v137
	v_exp_f32_e32 v139, v139
	v_add_f32_e32 v0, v0, v138
	v_exp_f32_e32 v140, v140
	v_add_f32_e32 v0, v0, v139
	v_exp_f32_e32 v141, v141
	v_add_f32_e32 v0, v0, v140
	v_exp_f32_e32 v142, v142
	v_add_f32_e32 v0, v0, v141
	v_exp_f32_e32 v143, v143
	v_add_f32_e32 v0, v0, v142
	v_exp_f32_e32 v144, v144
	v_add_f32_e32 v0, v0, v143
	v_exp_f32_e32 v145, v145
	v_add_f32_e32 v0, v0, v144
	v_cvt_pk_bf16_f32 v130, v130, v131
	v_cvt_pk_bf16_f32 v131, v132, v133
	v_cvt_pk_bf16_f32 v132, v134, v135
	v_cvt_pk_bf16_f32 v133, v136, v137
	v_cvt_pk_bf16_f32 v134, v138, v139
	v_cvt_pk_bf16_f32 v135, v140, v141
	v_cvt_pk_bf16_f32 v136, v142, v143
	v_add_f32_e32 v0, v0, v145
	v_cvt_pk_bf16_f32 v137, v144, v145
	v_add_f32_e32 v232, v232, v0
	v_exp_f32_e32 v146, v146
	v_exp_f32_e32 v147, v147
	v_exp_f32_e32 v148, v148
	v_add_f32_e32 v0, v146, v147
	v_exp_f32_e32 v149, v149
	v_add_f32_e32 v0, v0, v148
	v_exp_f32_e32 v150, v150
	v_add_f32_e32 v0, v0, v149
	v_exp_f32_e32 v151, v151
	v_add_f32_e32 v0, v0, v150
	v_exp_f32_e32 v152, v152
	v_add_f32_e32 v0, v0, v151
	v_exp_f32_e32 v153, v153
	v_add_f32_e32 v0, v0, v152
	v_exp_f32_e32 v154, v154
	v_add_f32_e32 v0, v0, v153
	v_exp_f32_e32 v155, v155
	v_add_f32_e32 v0, v0, v154
	v_exp_f32_e32 v156, v156
	v_add_f32_e32 v0, v0, v155
	v_exp_f32_e32 v157, v157
	v_add_f32_e32 v0, v0, v156
	v_exp_f32_e32 v158, v158
	v_add_f32_e32 v0, v0, v157
	v_exp_f32_e32 v159, v159
	v_add_f32_e32 v0, v0, v158
	v_exp_f32_e32 v160, v160
	v_add_f32_e32 v0, v0, v159
	v_exp_f32_e32 v161, v161
	v_add_f32_e32 v0, v0, v160
	v_cvt_pk_bf16_f32 v146, v146, v147
	v_cvt_pk_bf16_f32 v147, v148, v149
	v_cvt_pk_bf16_f32 v148, v150, v151
	v_cvt_pk_bf16_f32 v149, v152, v153
	v_cvt_pk_bf16_f32 v150, v154, v155
	v_cvt_pk_bf16_f32 v151, v156, v157
	v_cvt_pk_bf16_f32 v152, v158, v159
	v_add_f32_e32 v0, v0, v161
	v_cvt_pk_bf16_f32 v153, v160, v161
	v_add_f32_e32 v244, v244, v0
	s_waitcnt lgkmcnt(4)
	v_mfma_f32_16x16x32_bf16 v[114:117], v[162:165], v[130:133], v[114:117]
	v_mfma_f32_16x16x32_bf16 v[122:125], v[162:165], v[146:149], v[122:125]
	ds_read_b64_tr_b16 v[162:163], v242 offset:512
	ds_read_b64_tr_b16 v[164:165], v242 offset:8704
	v_mfma_f32_16x16x32_bf16 v[114:117], v[166:169], v[134:137], v[114:117]
	v_mfma_f32_16x16x32_bf16 v[122:125], v[166:169], v[150:153], v[122:125]
	ds_read_b64_tr_b16 v[166:167], v242 offset:16896
	ds_read_b64_tr_b16 v[168:169], v242 offset:25088
	s_waitcnt lgkmcnt(4)
	v_mfma_f32_16x16x32_bf16 v[118:121], v[170:173], v[130:133], v[118:121]
	v_mfma_f32_16x16x32_bf16 v[126:129], v[170:173], v[146:149], v[126:129]
	ds_read_b64_tr_b16 v[170:171], v242 offset:768
	ds_read_b64_tr_b16 v[172:173], v242 offset:8960
	v_mfma_f32_16x16x32_bf16 v[118:121], v[174:177], v[134:137], v[118:121]
	v_mfma_f32_16x16x32_bf16 v[126:129], v[174:177], v[150:153], v[126:129]
	ds_read_b64_tr_b16 v[174:175], v242 offset:17152
	ds_read_b64_tr_b16 v[176:177], v242 offset:25344
	s_waitcnt lgkmcnt(4)
	v_mfma_f32_16x16x32_bf16 v[98:101], v[162:165], v[130:133], v[98:101]
	v_mfma_f32_16x16x32_bf16 v[106:109], v[162:165], v[146:149], v[106:109]
	ds_read_b64_tr_b16 v[162:163], v242 offset:1024
	ds_read_b64_tr_b16 v[164:165], v242 offset:9216
	v_mfma_f32_16x16x32_bf16 v[98:101], v[166:169], v[134:137], v[98:101]
	v_mfma_f32_16x16x32_bf16 v[106:109], v[166:169], v[150:153], v[106:109]
	ds_read_b64_tr_b16 v[166:167], v242 offset:17408
	ds_read_b64_tr_b16 v[168:169], v242 offset:25600
	s_waitcnt lgkmcnt(4)
	v_mfma_f32_16x16x32_bf16 v[102:105], v[170:173], v[130:133], v[102:105]
	v_mfma_f32_16x16x32_bf16 v[110:113], v[170:173], v[146:149], v[110:113]
	ds_read_b64_tr_b16 v[170:171], v242 offset:1280
	ds_read_b64_tr_b16 v[172:173], v242 offset:9472
	v_mfma_f32_16x16x32_bf16 v[102:105], v[174:177], v[134:137], v[102:105]
	v_mfma_f32_16x16x32_bf16 v[110:113], v[174:177], v[150:153], v[110:113]
	ds_read_b64_tr_b16 v[174:175], v242 offset:17664
	ds_read_b64_tr_b16 v[176:177], v242 offset:25856
	s_waitcnt lgkmcnt(4)
	v_mfma_f32_16x16x32_bf16 v[82:85], v[162:165], v[130:133], v[82:85]
	v_mfma_f32_16x16x32_bf16 v[90:93], v[162:165], v[146:149], v[90:93]
	ds_read_b64_tr_b16 v[162:163], v242 offset:1536
	ds_read_b64_tr_b16 v[164:165], v242 offset:9728
	v_mfma_f32_16x16x32_bf16 v[82:85], v[166:169], v[134:137], v[82:85]
	v_mfma_f32_16x16x32_bf16 v[90:93], v[166:169], v[150:153], v[90:93]
	ds_read_b64_tr_b16 v[166:167], v242 offset:17920
	ds_read_b64_tr_b16 v[168:169], v242 offset:26112
	s_waitcnt lgkmcnt(4)
	v_mfma_f32_16x16x32_bf16 v[86:89], v[170:173], v[130:133], v[86:89]
	v_mfma_f32_16x16x32_bf16 v[94:97], v[170:173], v[146:149], v[94:97]
	ds_read_b64_tr_b16 v[170:171], v242 offset:1792
	ds_read_b64_tr_b16 v[172:173], v242 offset:9984
	v_mfma_f32_16x16x32_bf16 v[86:89], v[174:177], v[134:137], v[86:89]
	v_mfma_f32_16x16x32_bf16 v[94:97], v[174:177], v[150:153], v[94:97]
	ds_read_b64_tr_b16 v[174:175], v242 offset:18176
	ds_read_b64_tr_b16 v[176:177], v242 offset:26368
	s_waitcnt lgkmcnt(4)
	v_mfma_f32_16x16x32_bf16 v[66:69], v[162:165], v[130:133], v[66:69]
	v_mfma_f32_16x16x32_bf16 v[74:77], v[162:165], v[146:149], v[74:77]
	ds_read_b64_tr_b16 v[162:163], v242 offset:2048
	ds_read_b64_tr_b16 v[164:165], v242 offset:10240
	v_mfma_f32_16x16x32_bf16 v[66:69], v[166:169], v[134:137], v[66:69]
	v_mfma_f32_16x16x32_bf16 v[74:77], v[166:169], v[150:153], v[74:77]
	ds_read_b64_tr_b16 v[166:167], v242 offset:18432
	ds_read_b64_tr_b16 v[168:169], v242 offset:26624
	s_waitcnt lgkmcnt(4)
	v_mfma_f32_16x16x32_bf16 v[70:73], v[170:173], v[130:133], v[70:73]
	v_mfma_f32_16x16x32_bf16 v[78:81], v[170:173], v[146:149], v[78:81]
	ds_read_b64_tr_b16 v[170:171], v242 offset:2304
	ds_read_b64_tr_b16 v[172:173], v242 offset:10496
	v_mfma_f32_16x16x32_bf16 v[70:73], v[174:177], v[134:137], v[70:73]
	v_mfma_f32_16x16x32_bf16 v[78:81], v[174:177], v[150:153], v[78:81]
	ds_read_b64_tr_b16 v[174:175], v242 offset:18688
	ds_read_b64_tr_b16 v[176:177], v242 offset:26880
	s_waitcnt lgkmcnt(4)
	v_mfma_f32_16x16x32_bf16 v[50:53], v[162:165], v[130:133], v[50:53]
	v_mfma_f32_16x16x32_bf16 v[58:61], v[162:165], v[146:149], v[58:61]
	ds_read_b64_tr_b16 v[162:163], v242 offset:2560
	ds_read_b64_tr_b16 v[164:165], v242 offset:10752
	v_mfma_f32_16x16x32_bf16 v[50:53], v[166:169], v[134:137], v[50:53]
	v_mfma_f32_16x16x32_bf16 v[58:61], v[166:169], v[150:153], v[58:61]
	ds_read_b64_tr_b16 v[166:167], v242 offset:18944
	ds_read_b64_tr_b16 v[168:169], v242 offset:27136
	s_waitcnt lgkmcnt(4)
	v_mfma_f32_16x16x32_bf16 v[54:57], v[170:173], v[130:133], v[54:57]
	v_mfma_f32_16x16x32_bf16 v[62:65], v[170:173], v[146:149], v[62:65]
	ds_read_b64_tr_b16 v[170:171], v242 offset:2816
	ds_read_b64_tr_b16 v[172:173], v242 offset:11008
	v_mfma_f32_16x16x32_bf16 v[54:57], v[174:177], v[134:137], v[54:57]
	v_mfma_f32_16x16x32_bf16 v[62:65], v[174:177], v[150:153], v[62:65]
	ds_read_b64_tr_b16 v[174:175], v242 offset:19200
	ds_read_b64_tr_b16 v[176:177], v242 offset:27392
	s_waitcnt lgkmcnt(4)
	v_mfma_f32_16x16x32_bf16 v[34:37], v[162:165], v[130:133], v[34:37]
	v_mfma_f32_16x16x32_bf16 v[42:45], v[162:165], v[146:149], v[42:45]
	ds_read_b64_tr_b16 v[162:163], v242 offset:3072
	ds_read_b64_tr_b16 v[164:165], v242 offset:11264
	v_mfma_f32_16x16x32_bf16 v[34:37], v[166:169], v[134:137], v[34:37]
	v_mfma_f32_16x16x32_bf16 v[42:45], v[166:169], v[150:153], v[42:45]
	ds_read_b64_tr_b16 v[166:167], v242 offset:19456
	ds_read_b64_tr_b16 v[168:169], v242 offset:27648
	s_waitcnt lgkmcnt(4)
	v_mfma_f32_16x16x32_bf16 v[38:41], v[170:173], v[130:133], v[38:41]
	v_mfma_f32_16x16x32_bf16 v[46:49], v[170:173], v[146:149], v[46:49]
	ds_read_b64_tr_b16 v[170:171], v242 offset:3328
	ds_read_b64_tr_b16 v[172:173], v242 offset:11520
	v_mfma_f32_16x16x32_bf16 v[38:41], v[174:177], v[134:137], v[38:41]
	v_mfma_f32_16x16x32_bf16 v[46:49], v[174:177], v[150:153], v[46:49]
	ds_read_b64_tr_b16 v[174:175], v242 offset:19712
	ds_read_b64_tr_b16 v[176:177], v242 offset:27904
	s_waitcnt lgkmcnt(4)
	v_mfma_f32_16x16x32_bf16 v[18:21], v[162:165], v[130:133], v[18:21]
	v_mfma_f32_16x16x32_bf16 v[26:29], v[162:165], v[146:149], v[26:29]
	ds_read_b64_tr_b16 v[162:163], v242 offset:3584
	ds_read_b64_tr_b16 v[164:165], v242 offset:11776
	v_mfma_f32_16x16x32_bf16 v[18:21], v[166:169], v[134:137], v[18:21]
	v_mfma_f32_16x16x32_bf16 v[26:29], v[166:169], v[150:153], v[26:29]
	ds_read_b64_tr_b16 v[166:167], v242 offset:19968
	ds_read_b64_tr_b16 v[168:169], v242 offset:28160
	s_waitcnt lgkmcnt(4)
	v_mfma_f32_16x16x32_bf16 v[22:25], v[170:173], v[130:133], v[22:25]
	v_mfma_f32_16x16x32_bf16 v[30:33], v[170:173], v[146:149], v[30:33]
	ds_read_b64_tr_b16 v[170:171], v242 offset:3840
	ds_read_b64_tr_b16 v[172:173], v242 offset:12032
	v_mfma_f32_16x16x32_bf16 v[22:25], v[174:177], v[134:137], v[22:25]
	v_mfma_f32_16x16x32_bf16 v[30:33], v[174:177], v[150:153], v[30:33]
	ds_read_b64_tr_b16 v[174:175], v242 offset:20224
	ds_read_b64_tr_b16 v[176:177], v242 offset:28416
	s_waitcnt lgkmcnt(4)
	v_mfma_f32_16x16x32_bf16 v[2:5], v[162:165], v[130:133], v[2:5]
	v_mfma_f32_16x16x32_bf16 v[10:13], v[162:165], v[146:149], v[10:13]
	v_mfma_f32_16x16x32_bf16 v[2:5], v[166:169], v[134:137], v[2:5]
	v_mfma_f32_16x16x32_bf16 v[10:13], v[166:169], v[150:153], v[10:13]
	s_waitcnt lgkmcnt(0)
	v_mfma_f32_16x16x32_bf16 v[6:9], v[170:173], v[130:133], v[6:9]
	v_mfma_f32_16x16x32_bf16 v[14:17], v[170:173], v[146:149], v[14:17]
	v_mfma_f32_16x16x32_bf16 v[6:9], v[174:177], v[134:137], v[6:9]
	v_mfma_f32_16x16x32_bf16 v[14:17], v[174:177], v[150:153], v[14:17]
	s_xor_b32 s4, s70, 0x10000
	v_xor_b32_e32 v234, s4, v221
	v_xor_b32_e32 v235, 64, v234
	v_xor_b32_e32 v236, 0x80, v234
	v_xor_b32_e32 v237, 0xc0, v234
	s_branch .Lat_end_a

.Lat_end_a:
.Lat_next:
	s_add_i32 s58, s58, 1
	s_xor_b32 s70, s70, 0x10000
	s_xor_b32 s71, s71, 0x10000
	v_add_u32_e32 v223, 0xffffffc0, v223
	s_addk_i32 s91, 0x40
	s_add_u32 s50, s50, 0x80000
	s_addc_u32 s51, s51, 0
	s_mov_b32 s94, 0
	s_cmp_le_u32 s58, s88
	s_cbranch_scc1 .Lat_loop
	s_waitcnt vmcnt(0) lgkmcnt(0)
	s_barrier
	s_cmp_gt_u32 s58, s89
	s_cbranch_scc1 .Lat_done
	ds_read_b128 v[162:165], v234
	ds_read_b128 v[166:169], v235
	ds_read_b128 v[170:173], v236
	ds_read_b128 v[174:177], v237
	v_add_u32_e32 v242, s70, v222
	s_waitcnt lgkmcnt(2)
	v_mfma_f32_16x16x32_bf16 v[130:133], v[162:165], v[178:181], v[246:249]
	v_mfma_f32_16x16x32_bf16 v[146:149], v[162:165], v[194:197], v[250:253]
	ds_read_b128 v[162:165], v234 offset:4096
	v_mfma_f32_16x16x32_bf16 v[130:133], v[166:169], v[182:185], v[130:133]
	v_mfma_f32_16x16x32_bf16 v[146:149], v[166:169], v[198:201], v[146:149]
	ds_read_b128 v[166:169], v235 offset:4096
	s_waitcnt lgkmcnt(2)
	v_mfma_f32_16x16x32_bf16 v[130:133], v[170:173], v[186:189], v[130:133]
	v_mfma_f32_16x16x32_bf16 v[146:149], v[170:173], v[202:205], v[146:149]
	ds_read_b128 v[170:173], v236 offset:4096
	v_mfma_f32_16x16x32_bf16 v[130:133], v[174:177], v[190:193], v[130:133]
	v_mfma_f32_16x16x32_bf16 v[146:149], v[174:177], v[206:209], v[146:149]
	ds_read_b128 v[174:177], v237 offset:4096
	s_waitcnt lgkmcnt(2)
	v_mfma_f32_16x16x32_bf16 v[134:137], v[162:165], v[178:181], v[246:249]
	v_mfma_f32_16x16x32_bf16 v[150:153], v[162:165], v[194:197], v[250:253]
	ds_read_b128 v[162:165], v234 offset:8192
	v_mfma_f32_16x16x32_bf16 v[134:137], v[166:169], v[182:185], v[134:137]
	v_mfma_f32_16x16x32_bf16 v[150:153], v[166:169], v[198:201], v[150:153]
	ds_read_b128 v[166:169], v235 offset:8192
	s_waitcnt lgkmcnt(2)
	v_mfma_f32_16x16x32_bf16 v[134:137], v[170:173], v[186:189], v[134:137]
	v_mfma_f32_16x16x32_bf16 v[150:153], v[170:173], v[202:205], v[150:153]
	ds_read_b128 v[170:173], v236 offset:8192
	v_mfma_f32_16x16x32_bf16 v[134:137], v[174:177], v[190:193], v[134:137]
	v_mfma_f32_16x16x32_bf16 v[150:153], v[174:177], v[206:209], v[150:153]
	ds_read_b128 v[174:177], v237 offset:8192
	s_waitcnt lgkmcnt(2)
	v_mfma_f32_16x16x32_bf16 v[138:141], v[162:165], v[178:181], v[246:249]
	v_mfma_f32_16x16x32_bf16 v[154:157], v[162:165], v[194:197], v[250:253]
	ds_read_b128 v[162:165], v234 offset:12288
	v_mfma_f32_16x16x32_bf16 v[138:141], v[166:169], v[182:185], v[138:141]
	v_mfma_f32_16x16x32_bf16 v[154:157], v[166:169], v[198:201], v[154:157]
	ds_read_b128 v[166:169], v235 offset:12288
	s_waitcnt lgkmcnt(2)
	v_mfma_f32_16x16x32_bf16 v[138:141], v[170:173], v[186:189], v[138:141]
	v_mfma_f32_16x16x32_bf16 v[154:157], v[170:173], v[202:205], v[154:157]
	ds_read_b128 v[170:173], v236 offset:12288
	v_mfma_f32_16x16x32_bf16 v[138:141], v[174:177], v[190:193], v[138:141]
	v_mfma_f32_16x16x32_bf16 v[154:157], v[174:177], v[206:209], v[154:157]
	ds_read_b128 v[174:177], v237 offset:12288
	s_waitcnt lgkmcnt(2)
	v_mfma_f32_16x16x32_bf16 v[142:145], v[162:165], v[178:181], v[246:249]
	v_mfma_f32_16x16x32_bf16 v[158:161], v[162:165], v[194:197], v[250:253]
	ds_read_b64_tr_b16 v[162:163], v242 offset:0
	ds_read_b64_tr_b16 v[164:165], v242 offset:8192
	v_mfma_f32_16x16x32_bf16 v[142:145], v[166:169], v[182:185], v[142:145]
	v_mfma_f32_16x16x32_bf16 v[158:161], v[166:169], v[198:201], v[158:161]
	ds_read_b64_tr_b16 v[166:167], v242 offset:16384
	ds_read_b64_tr_b16 v[168:169], v242 offset:24576
	s_waitcnt lgkmcnt(4)
	v_mfma_f32_16x16x32_bf16 v[142:145], v[170:173], v[186:189], v[142:145]
	v_mfma_f32_16x16x32_bf16 v[158:161], v[170:173], v[202:205], v[158:161]
	ds_read_b64_tr_b16 v[170:171], v242 offset:256
	ds_read_b64_tr_b16 v[172:173], v242 offset:8448
	v_mfma_f32_16x16x32_bf16 v[142:145], v[174:177], v[190:193], v[142:145]
	v_mfma_f32_16x16x32_bf16 v[158:161], v[174:177], v[206:209], v[158:161]
	ds_read_b64_tr_b16 v[174:175], v242 offset:16640
	ds_read_b64_tr_b16 v[176:177], v242 offset:24832
	s_add_i32 s4, s91, 0xb0
	s_cmp_le_u32 s4, s3
	s_cbranch_scc0 .Lat_diag_b
